# out_proj idle workgroups: second transpose pass first, x prefetch afterwards (closer to the epilogues that use it)
# baseline (speedup 1.0000x reference)
.Lp6_ret:
	s_mov_b64 exec, -1
	s_cmpk_eq_i32 s32, 0xff
	s_cbranch_scc1 .LBB0_1182
	s_mov_b64 s[14:15], 0
	v_readfirstlane_b32 s45, v170
	s_branch .Lpf7
